# v37 plus thresholded o-rescale in attention interior loop and pipelined V-fragment reads in boundary-tile PV
# speedup vs baseline: 1.0043x; 1.0024x over previous
; #define LAS __attribute__((address_space(3)))
; __device__ __forceinline__ unsigned cvtpk(float lo, float hi) { unsigned r; asm volatile("v_cvt_pk_bf16_f32 %0, %1, %2" : "=v"(r) : "v"(lo), "v"(hi)); return r; }
; __device__ __forceinline__ void attn_item(LAS unsigned char* lds, const bf16_t* Z, bf16_t* Y, const float* logf, const float* ksum, const float* rel_bias,
;                                           const int moba, const int b, const int h, const int qt) {
;     ...
;             float tm = fmaxf(s0[0], s1[0]);
; #pragma unroll
;             for (int i = 1; i < 16; ++i) tm = fmaxf(tm, fmaxf(s0[i], s1[i]));
;             tm = fmaxf(tm, __shfl_xor(tm, 32));
;             const float mnew = fmaxf(mrun, tm);
;             const float muse = (mnew == -INFINITY) ? 0.f : mnew;
;             const float alpha = __builtin_amdgcn_exp2f(mrun - muse);
;             mrun = mnew;
;             float ps = 0.f;
; #pragma unroll
;             for (int i = 0; i < 16; ++i) { s0[i] = __builtin_amdgcn_exp2f(s0[i] - muse); s1[i] = __builtin_amdgcn_exp2f(s1[i] - muse); ps += s0[i] + s1[i]; }
;             lsum = lsum * alpha + ps;
;             o0 *= alpha; o1 *= alpha; o2 *= alpha; o3 *= alpha;
;             bf16x8 pb[4];
;             { u32x4 w;
;               w.x = cvtpk(s0[0], s0[1]); w.y = cvtpk(s0[2], s0[3]); w.z = cvtpk(s0[4], s0[5]); w.w = cvtpk(s0[6], s0[7]); pb[0] = __builtin_bit_cast(bf16x8, w);
;               w.x = cvtpk(s0[8], s0[9]); w.y = cvtpk(s0[10], s0[11]); w.z = cvtpk(s0[12], s0[13]); w.w = cvtpk(s0[14], s0[15]); pb[1] = __builtin_bit_cast(bf16x8, w);
;               w.x = cvtpk(s1[0], s1[1]); w.y = cvtpk(s1[2], s1[3]); w.z = cvtpk(s1[4], s1[5]); w.w = cvtpk(s1[6], s1[7]); pb[2] = __builtin_bit_cast(bf16x8, w);
;               w.x = cvtpk(s1[8], s1[9]); w.y = cvtpk(s1[10], s1[11]); w.z = cvtpk(s1[12], s1[13]); w.w = cvtpk(s1[14], s1[15]); pb[3] = __builtin_bit_cast(bf16x8, w); }
; #pragma unroll
;             for (int c = 0; c < 4; ++c) {
;                 const LAS unsigned char* vp = lds + V_BASE + vcur * VB_SZ + vroff + (16 * c) * VSTR;
.LBB0_188:
	v_max_f32_e32 v17, v115, v115
	v_max_f32_e32 v18, v147, v147
	v_max_f32_e32 v17, v18, v17
	v_max_f32_e32 v18, v116, v116
	v_max_f32_e32 v19, v148, v148
	v_max_f32_e32 v18, v19, v18
	v_max_f32_e32 v19, v117, v117
	v_max_f32_e32 v20, v149, v149
	v_max3_f32 v17, v146, v114, v17
	v_max_f32_e32 v19, v20, v19
	v_max3_f32 v17, v17, v18, v19
	v_max_f32_e32 v18, v118, v118
	v_max_f32_e32 v19, v150, v150
	v_max_f32_e32 v18, v19, v18
	v_max_f32_e32 v19, v119, v119
	v_max_f32_e32 v20, v151, v151
	v_max_f32_e32 v19, v20, v19
	v_max3_f32 v17, v17, v18, v19
	v_max_f32_e32 v18, v120, v120
	v_max_f32_e32 v19, v152, v152
	v_max_f32_e32 v18, v19, v18
	v_max_f32_e32 v19, v121, v121
	v_max_f32_e32 v20, v153, v153
	v_max_f32_e32 v19, v20, v19
	v_max3_f32 v17, v17, v18, v19
	v_max_f32_e32 v18, v122, v122
	v_max_f32_e32 v19, v154, v154
	v_max_f32_e32 v18, v19, v18
	v_max_f32_e32 v19, v123, v123
	v_max_f32_e32 v20, v155, v155
	v_max_f32_e32 v19, v20, v19
	v_max3_f32 v17, v17, v18, v19
	v_max_f32_e32 v18, v124, v124
	v_max_f32_e32 v19, v156, v156
	v_max_f32_e32 v18, v19, v18
	v_max_f32_e32 v19, v125, v125
	v_max_f32_e32 v20, v157, v157
	v_max_f32_e32 v19, v20, v19
	v_max3_f32 v17, v17, v18, v19
	v_max_f32_e32 v18, v126, v126
	v_max_f32_e32 v19, v158, v158
	v_max_f32_e32 v18, v19, v18
	v_max_f32_e32 v19, v127, v127
	v_max_f32_e32 v20, v159, v159
	v_max_f32_e32 v19, v20, v19
	v_max3_f32 v17, v17, v18, v19
	v_max_f32_e32 v18, v128, v128
	v_max_f32_e32 v19, v160, v160
	v_max_f32_e32 v18, v19, v18
	v_max_f32_e32 v19, v129, v129
	v_max_f32_e32 v20, v161, v161
	v_max_f32_e32 v19, v20, v19
	v_max3_f32 v17, v17, v18, v19
	v_and_b32_e32 v19, 64, v229
	v_xor_b32_e32 v18, 32, v229
	v_add_u32_e32 v19, 64, v19
	v_cmp_lt_i32_e32 vcc, v18, v19
	s_mul_i32 s4, s37, 0x5000
	s_nop 0
	v_cndmask_b32_e32 v18, v229, v18, vcc
	v_lshlrev_b32_e32 v18, 2, v18
	ds_bpermute_b32 v18, v18, v17
	s_waitcnt lgkmcnt(0)
	v_max3_f32 v17, v234, v17, v18
	v_cmp_neq_f32_e32 vcc, s34, v17
	s_nop 1
	v_cndmask_b32_e32 v18, 0, v17, vcc
	v_sub_f32_e32 v20, v146, v18
	v_exp_f32_e32 v27, v20
	v_sub_f32_e32 v20, v114, v18
	v_exp_f32_e32 v105, v20
	v_sub_f32_e32 v20, v147, v18
	v_exp_f32_e32 v26, v20
	v_sub_f32_e32 v20, v115, v18
	v_exp_f32_e32 v28, v20
	v_sub_f32_e32 v20, v148, v18
	v_exp_f32_e32 v29, v20
	v_sub_f32_e32 v20, v116, v18
	v_exp_f32_e32 v31, v20
	v_sub_f32_e32 v20, v149, v18
	v_exp_f32_e32 v30, v20
	v_sub_f32_e32 v20, v117, v18
	v_exp_f32_e32 v98, v20
	v_sub_f32_e32 v20, v150, v18
	v_exp_f32_e32 v99, v20
	v_sub_f32_e32 v20, v118, v18
	v_exp_f32_e32 v101, v20
	v_sub_f32_e32 v20, v151, v18
	v_exp_f32_e32 v100, v20
	v_sub_f32_e32 v20, v119, v18
	v_exp_f32_e32 v102, v20
	v_sub_f32_e32 v20, v152, v18
	v_exp_f32_e32 v103, v20
	v_sub_f32_e32 v20, v120, v18
	v_exp_f32_e32 v107, v20
	v_sub_f32_e32 v20, v153, v18
	v_exp_f32_e32 v104, v20
	v_sub_f32_e32 v20, v121, v18
	v_exp_f32_e32 v106, v20
	v_sub_f32_e32 v20, v154, v18
	v_exp_f32_e32 v109, v20
	v_sub_f32_e32 v20, v122, v18
	v_exp_f32_e32 v111, v20
	v_sub_f32_e32 v20, v155, v18
	v_exp_f32_e32 v108, v20
	v_sub_f32_e32 v20, v123, v18
	v_exp_f32_e32 v110, v20
	v_sub_f32_e32 v20, v156, v18
	v_exp_f32_e32 v113, v20
	v_sub_f32_e32 v20, v124, v18
	v_exp_f32_e32 v115, v20
	v_sub_f32_e32 v20, v157, v18
	v_exp_f32_e32 v112, v20
	v_sub_f32_e32 v20, v125, v18
	v_exp_f32_e32 v114, v20
	v_sub_f32_e32 v20, v158, v18
	v_exp_f32_e32 v117, v20
	v_sub_f32_e32 v20, v126, v18
	v_exp_f32_e32 v119, v20
	v_sub_f32_e32 v20, v159, v18
	v_exp_f32_e32 v116, v20
	v_sub_f32_e32 v20, v127, v18
	v_exp_f32_e32 v118, v20
	v_sub_f32_e32 v20, v160, v18
	v_exp_f32_e32 v121, v20
	v_sub_f32_e32 v20, v128, v18
	v_sub_f32_e32 v19, v234, v18
	v_exp_f32_e32 v123, v20
	v_sub_f32_e32 v20, v161, v18
	v_sub_f32_e32 v18, v129, v18
	v_add_u32_e32 v125, s4, v232
	v_exp_f32_e32 v120, v19
	v_exp_f32_e32 v122, v20
	v_exp_f32_e32 v124, v18
	v_cvt_pk_bf16_f32 v126, v27, v26
	v_cvt_pk_bf16_f32 v127, v29, v30
	v_cvt_pk_bf16_f32 v128, v99, v100
	v_cvt_pk_bf16_f32 v129, v103, v104
	v_cvt_pk_bf16_f32 v130, v109, v108
	v_cvt_pk_bf16_f32 v131, v113, v112
	v_cvt_pk_bf16_f32 v132, v117, v116
	v_cvt_pk_bf16_f32 v133, v121, v122
	v_cvt_pk_bf16_f32 v22, v105, v28
	v_cvt_pk_bf16_f32 v23, v31, v98
	v_cvt_pk_bf16_f32 v24, v101, v102
	v_cvt_pk_bf16_f32 v25, v107, v106
	v_cvt_pk_bf16_f32 v18, v111, v110
	v_cvt_pk_bf16_f32 v19, v115, v114
	v_cvt_pk_bf16_f32 v20, v119, v118
	v_cvt_pk_bf16_f32 v21, v123, v124
	ds_read_b64_tr_b16 v[134:135], v125 offset:34816
	ds_read_b64_tr_b16 v[136:137], v125 offset:37376
	ds_read_b64_tr_b16 v[138:139], v125 offset:34880
	ds_read_b64_tr_b16 v[140:141], v125 offset:37440
	v_pk_mul_f32 v[48:49], v[48:49], v[120:121] op_sel_hi:[1,0]
	v_pk_mul_f32 v[46:47], v[46:47], v[120:121] op_sel_hi:[1,0]
	v_pk_mul_f32 v[44:45], v[44:45], v[120:121] op_sel_hi:[1,0]
	v_pk_mul_f32 v[42:43], v[42:43], v[120:121] op_sel_hi:[1,0]
	v_pk_mul_f32 v[40:41], v[40:41], v[120:121] op_sel_hi:[1,0]
	v_pk_mul_f32 v[38:39], v[38:39], v[120:121] op_sel_hi:[1,0]
	v_pk_mul_f32 v[36:37], v[36:37], v[120:121] op_sel_hi:[1,0]
	v_pk_mul_f32 v[34:35], v[34:35], v[120:121] op_sel_hi:[1,0]
	v_pk_mul_f32 v[96:97], v[96:97], v[120:121] op_sel_hi:[1,0]
	v_pk_mul_f32 v[94:95], v[94:95], v[120:121] op_sel_hi:[1,0]
	v_pk_mul_f32 v[92:93], v[92:93], v[120:121] op_sel_hi:[1,0]
	v_pk_mul_f32 v[90:91], v[90:91], v[120:121] op_sel_hi:[1,0]
	v_pk_mul_f32 v[88:89], v[88:89], v[120:121] op_sel_hi:[1,0]
	v_pk_mul_f32 v[86:87], v[86:87], v[120:121] op_sel_hi:[1,0]
	v_pk_mul_f32 v[84:85], v[84:85], v[120:121] op_sel_hi:[1,0]
	v_pk_mul_f32 v[82:83], v[82:83], v[120:121] op_sel_hi:[1,0]
	s_waitcnt lgkmcnt(2)
; #define LAS __attribute__((address_space(3)))
; __device__ __forceinline__ unsigned cvtpk(float lo, float hi) { unsigned r; asm volatile("v_cvt_pk_bf16_f32 %0, %1, %2" : "=v"(r) : "v"(lo), "v"(hi)); return r; }
; #define ATT_PV(db, od) { const s16x4 lo = vtr(vp + 64 * (db)), hi = vtr(vp + 8 * VSTR + 64 * (db)); const bf16x8 A = __builtin_shufflevector(lo, hi, 0, 1, 2, 3, 4, 5, 6, 7); od = mfma32(A, pb[c], od); }
; __device__ __forceinline__ void attn_item(LAS unsigned char* lds, const bf16_t* Z, bf16_t* Y, const float* logf, const float* ksum, const float* rel_bias,
;                                           const int moba, const int b, const int h, const int qt) {
;     ...
;             for (int i = 0; i < 16; ++i) { s0[i] = __builtin_amdgcn_exp2f(s0[i] - muse); s1[i] = __builtin_amdgcn_exp2f(s1[i] - muse); ps += s0[i] + s1[i]; }
;             lsum = lsum * alpha + ps;
;             o0 *= alpha; o1 *= alpha; o2 *= alpha; o3 *= alpha;
;             bf16x8 pb[4];
;             { u32x4 w;
;               w.x = cvtpk(s0[0], s0[1]); w.y = cvtpk(s0[2], s0[3]); w.z = cvtpk(s0[4], s0[5]); w.w = cvtpk(s0[6], s0[7]); pb[0] = __builtin_bit_cast(bf16x8, w);
;               w.x = cvtpk(s0[8], s0[9]); w.y = cvtpk(s0[10], s0[11]); w.z = cvtpk(s0[12], s0[13]); w.w = cvtpk(s0[14], s0[15]); pb[1] = __builtin_bit_cast(bf16x8, w);
;               w.x = cvtpk(s1[0], s1[1]); w.y = cvtpk(s1[2], s1[3]); w.z = cvtpk(s1[4], s1[5]); w.w = cvtpk(s1[6], s1[7]); pb[2] = __builtin_bit_cast(bf16x8, w);
;               w.x = cvtpk(s1[8], s1[9]); w.y = cvtpk(s1[10], s1[11]); w.z = cvtpk(s1[12], s1[13]); w.w = cvtpk(s1[14], s1[15]); pb[3] = __builtin_bit_cast(bf16x8, w); }
; #pragma unroll
;             for (int c = 0; c < 4; ++c) {
;                 const LAS unsigned char* vp = lds + V_BASE + vcur * VB_SZ + vroff + (16 * c) * VSTR;
;     ...
;                 ATT_PV(0, o0) ATT_PV(1, o1) ATT_PV(2, o2) ATT_PV(3, o3)
;     ...
;             }
	v_mfma_f32_32x32x16_bf16 v[34:49], v[134:137], v[126:129], v[34:49]
	ds_read_b64_tr_b16 v[134:135], v125 offset:34944
	ds_read_b64_tr_b16 v[136:137], v125 offset:37504
	v_mul_f32_e64 v80, v80, v120
	v_mul_f32_e64 v81, v81, v120
	v_mul_f32_e64 v78, v78, v120
	v_mul_f32_e64 v79, v79, v120
	v_pk_mul_f32 v[76:77], v[76:77], v[120:121] op_sel_hi:[1,0]
	v_pk_mul_f32 v[74:75], v[74:75], v[120:121] op_sel_hi:[1,0]
	v_pk_mul_f32 v[72:73], v[72:73], v[120:121] op_sel_hi:[1,0]
	v_pk_mul_f32 v[70:71], v[70:71], v[120:121] op_sel_hi:[1,0]
	s_waitcnt lgkmcnt(2)
	v_mfma_f32_32x32x16_bf16 v[82:97], v[138:141], v[126:129], v[82:97]
	ds_read_b64_tr_b16 v[138:139], v125 offset:35008
	ds_read_b64_tr_b16 v[140:141], v125 offset:37568
	v_mul_f32_e64 v68, v68, v120
	v_mul_f32_e64 v69, v69, v120
	v_mul_f32_e64 v66, v66, v120
	v_mul_f32_e64 v67, v67, v120
	v_pk_mul_f32 v[64:65], v[64:65], v[120:121] op_sel_hi:[1,0]
	v_pk_mul_f32 v[62:63], v[62:63], v[120:121] op_sel_hi:[1,0]
	v_pk_mul_f32 v[60:61], v[60:61], v[120:121] op_sel_hi:[1,0]
	v_pk_mul_f32 v[58:59], v[58:59], v[120:121] op_sel_hi:[1,0]
	v_pk_mul_f32 v[56:57], v[56:57], v[120:121] op_sel_hi:[1,0]
	v_pk_mul_f32 v[54:55], v[54:55], v[120:121] op_sel_hi:[1,0]
	v_pk_mul_f32 v[52:53], v[52:53], v[120:121] op_sel_hi:[1,0]
	v_pk_mul_f32 v[50:51], v[50:51], v[120:121] op_sel_hi:[1,0]
	s_waitcnt lgkmcnt(2)
	v_mfma_f32_32x32x16_bf16 v[66:81], v[134:137], v[126:129], v[66:81]
	v_add_f32_e32 v27, v27, v105
	v_add_f32_e32 v31, v29, v31
	v_mov_b32_e32 v29, v0
	v_add_f32_e32 v101, v99, v101
	v_add_f32_e32 v105, v103, v107
	v_add_f32_e32 v109, v109, v111
	v_add_f32_e32 v113, v113, v115
	s_waitcnt lgkmcnt(0)
	v_mfma_f32_32x32x16_bf16 v[50:65], v[138:141], v[126:129], v[50:65]
	ds_read_b64_tr_b16 v[126:127], v125 offset:39936
	ds_read_b64_tr_b16 v[128:129], v125 offset:42496
	ds_read_b64_tr_b16 v[134:135], v125 offset:40000
	ds_read_b64_tr_b16 v[136:137], v125 offset:42560
	ds_read_b64_tr_b16 v[138:139], v125 offset:40064
	ds_read_b64_tr_b16 v[140:141], v125 offset:42624
	v_add_f32_e32 v117, v117, v119
	v_add_f32_e32 v123, v121, v123
	v_mov_b32_e32 v234, v17
	s_waitcnt lgkmcnt(4)
	v_mfma_f32_32x32x16_bf16 v[34:49], v[126:129], v[130:133], v[34:49]
	ds_read_b64_tr_b16 v[126:127], v125 offset:40128
	ds_read_b64_tr_b16 v[128:129], v125 offset:42688
	s_waitcnt lgkmcnt(4)
	v_mfma_f32_32x32x16_bf16 v[82:97], v[134:137], v[130:133], v[82:97]
	ds_read_b64_tr_b16 v[134:135], v125 offset:45056
	ds_read_b64_tr_b16 v[136:137], v125 offset:47616
	s_waitcnt lgkmcnt(4)
	v_mfma_f32_32x32x16_bf16 v[66:81], v[138:141], v[130:133], v[66:81]
	ds_read_b64_tr_b16 v[138:139], v125 offset:45120
	ds_read_b64_tr_b16 v[140:141], v125 offset:47680
	s_waitcnt lgkmcnt(4)
	v_mfma_f32_32x32x16_bf16 v[50:65], v[126:129], v[130:133], v[50:65]
	ds_read_b64_tr_b16 v[126:127], v125 offset:45184
	ds_read_b64_tr_b16 v[128:129], v125 offset:47744
	s_waitcnt lgkmcnt(4)
	v_mfma_f32_32x32x16_bf16 v[34:49], v[134:137], v[22:25], v[34:49]
	ds_read_b64_tr_b16 v[134:135], v125 offset:45248
	ds_read_b64_tr_b16 v[136:137], v125 offset:47808
	s_waitcnt lgkmcnt(4)
	v_mfma_f32_32x32x16_bf16 v[82:97], v[138:141], v[22:25], v[82:97]
	ds_read_b64_tr_b16 v[138:139], v125 offset:50176
	ds_read_b64_tr_b16 v[140:141], v125 offset:52736
	s_waitcnt lgkmcnt(4)
	v_mfma_f32_32x32x16_bf16 v[66:81], v[126:129], v[22:25], v[66:81]
	ds_read_b64_tr_b16 v[126:127], v125 offset:50240
	ds_read_b64_tr_b16 v[128:129], v125 offset:52800
	s_waitcnt lgkmcnt(4)
	v_mfma_f32_32x32x16_bf16 v[50:65], v[134:137], v[22:25], v[50:65]
	ds_read_b64_tr_b16 v[134:135], v125 offset:50304
	ds_read_b64_tr_b16 v[136:137], v125 offset:52864
	s_waitcnt lgkmcnt(4)
	v_mfma_f32_32x32x16_bf16 v[34:49], v[138:141], v[18:21], v[34:49]
	ds_read_b64_tr_b16 v[138:139], v125 offset:50368
	ds_read_b64_tr_b16 v[140:141], v125 offset:52928
	s_waitcnt lgkmcnt(4)
	v_mfma_f32_32x32x16_bf16 v[82:97], v[126:129], v[18:21], v[82:97]
	s_waitcnt lgkmcnt(2)
	v_mfma_f32_32x32x16_bf16 v[66:81], v[134:137], v[18:21], v[66:81]
	s_waitcnt lgkmcnt(0)
	v_mfma_f32_32x32x16_bf16 v[50:65], v[138:141], v[18:21], v[50:65]
	v_add_f32_e64 v18, v26, v28
	v_add_f32_e64 v19, v27, v29
	v_pk_add_f32 v[18:19], v[18:19], v[18:19] op_sel_hi:[0,1]
	v_mov_b32_e32 v99, v19
	v_pk_add_f32 v[18:19], v[30:31], v[98:99]
	s_nop 0
	v_pk_add_f32 v[18:19], v[18:19], v[18:19] op_sel_hi:[0,1]
	v_mov_b32_e32 v103, v19
	v_pk_add_f32 v[18:19], v[100:101], v[102:103]
	s_nop 0
	v_pk_add_f32 v[18:19], v[18:19], v[18:19] op_sel_hi:[0,1]
	v_mov_b32_e32 v107, v19
	v_pk_add_f32 v[18:19], v[104:105], v[106:107]
	s_nop 0
	v_pk_add_f32 v[18:19], v[18:19], v[18:19] op_sel_hi:[0,1]
	v_mov_b32_e32 v111, v19
	v_pk_add_f32 v[18:19], v[108:109], v[110:111]
	s_nop 0
	v_pk_add_f32 v[18:19], v[18:19], v[18:19] op_sel_hi:[0,1]
	v_mov_b32_e32 v115, v19
	v_pk_add_f32 v[18:19], v[112:113], v[114:115]
	s_nop 0
	v_pk_add_f32 v[18:19], v[18:19], v[18:19] op_sel_hi:[0,1]
	v_mov_b32_e32 v119, v19
	v_pk_add_f32 v[18:19], v[116:117], v[118:119]
	s_nop 0
	v_pk_add_f32 v[18:19], v[18:19], v[18:19] op_sel_hi:[0,1]
	v_mov_b32_e32 v125, v19
	v_pk_add_f32 v[18:19], v[122:123], v[124:125]
	s_nop 0
	v_add_f32_e32 v18, v18, v19
	v_fmac_f32_e32 v18, v233, v120
	v_mov_b32_e32 v233, v18
